# planA + write-through (sc1) stores in gate-up epilogue
# baseline (speedup 1.0000x reference)
; __device__ __forceinline__ unsigned cvt_pk_bf16(float lo, float hi) { unsigned r; asm volatile("v_cvt_pk_bf16_f32 %0, %1, %2" : "=v"(r) : "v"(lo), "v"(hi)); return r; }
;     __device__ __forceinline__ void operator()(const f32x4 (&acc)[2][2][4][2], const Unit& u, int wr, int wc, int fr, int fq, const float (&sv)[8]) const {
;     ...
;                 const float rinv = __builtin_amdgcn_rsqf(sv[ai * 4 + m] * (1.f / DM) + EPS), rneg = rinv * -1.44269504f, r2 = rinv * rinv;
;                 const f32x4 g0 = acc[ai][0][m][0], g1 = acc[ai][0][m][1], u0 = acc[ai][1][m][0], u1 = acc[ai][1][m][1];
;                 f32x4 e0, e1;
; #pragma unroll
;                 for (int j = 0; j < 4; ++j) { e0[j] = __builtin_amdgcn_rcpf(1.f + __builtin_amdgcn_exp2f(g0[j] * rneg)); e1[j] = __builtin_amdgcn_rcpf(1.f + __builtin_amdgcn_exp2f(g1[j] * rneg)); }
;                 const f32x4 a0 = (g0 * u0) * (e0 * r2), a1 = (g1 * u1) * (e1 * r2);
;                 u32x4 w;
;                 w.x = cvt_pk_bf16(a0[0], a0[1]); w.y = cvt_pk_bf16(a0[2], a0[3]); w.z = cvt_pk_bf16(a1[0], a1[1]); w.w = cvt_pk_bf16(a1[2], a1[3]);
;                 *(u32x4*)(O + (size_t)row * DFF + col0) = w;
.LBB0_137:
	s_lshl_b32 s13, s51, 10
	s_and_b32 s13, s13, 0x400
	v_add_u32_e32 v140, s13, v149
	ds_read2_b32 v[152:153], v140 offset1:16
	v_pk_mul_f32 v[118:119], v[126:127], v[118:119]
	v_pk_mul_f32 v[116:117], v[124:125], v[116:117]
	v_pk_mul_f32 v[114:115], v[122:123], v[114:115]
	v_pk_mul_f32 v[112:113], v[120:121], v[112:113]
	s_waitcnt lgkmcnt(0)
	v_fmamk_f32 v141, v152, 0x3a000000, v218
	v_rsq_f32_e32 v152, v141
	ds_read2_b32 v[144:145], v140 offset0:32 offset1:48
	ds_read2_b32 v[142:143], v140 offset0:128 offset1:144
	v_lshl_or_b32 v154, s49, 7, v148
	v_lshl_add_u32 v151, s50, 8, v146
	v_mul_f32_e32 v161, 0xbfb8aa3b, v152
	v_mul_f32_e32 v141, v124, v161
	v_mul_f32_e32 v156, v120, v161
	v_exp_f32_e32 v157, v141
	v_exp_f32_e32 v156, v156
	v_mul_f32_e32 v158, v125, v161
	v_mul_f32_e32 v162, v122, v161
	v_add_f32_e32 v157, 1.0, v157
	v_add_f32_e32 v159, 1.0, v156
	v_rcp_f32_e32 v156, v157
	v_exp_f32_e32 v157, v158
	v_mul_f32_e32 v158, v121, v161
	v_exp_f32_e32 v160, v158
	v_rcp_f32_e32 v158, v159
	v_mul_f32_e32 v163, v127, v161
	v_exp_f32_e32 v162, v162
	v_add_f32_e32 v159, 1.0, v160
	v_mul_f32_e32 v160, v126, v161
	v_mul_f32_e32 v161, v123, v161
	v_exp_f32_e32 v160, v160
	v_exp_f32_e32 v163, v163
	v_exp_f32_e32 v164, v161
	v_add_f32_e32 v157, 1.0, v157
	v_add_f32_e32 v160, 1.0, v160
	v_add_f32_e32 v162, 1.0, v162
	v_add_f32_e32 v161, 1.0, v163
	v_add_f32_e32 v163, 1.0, v164
	v_rcp_f32_e32 v157, v157
	v_rcp_f32_e32 v160, v160
	v_rcp_f32_e32 v162, v162
	v_rcp_f32_e32 v161, v161
	v_rcp_f32_e32 v163, v163
	v_rcp_f32_e32 v159, v159
	v_mul_f32_e32 v152, v152, v152
	v_pk_mul_f32 v[124:125], v[152:153], v[156:157] op_sel_hi:[0,1]
	v_pk_mul_f32 v[126:127], v[152:153], v[160:161] op_sel_hi:[0,1]
	v_pk_mul_f32 v[122:123], v[152:153], v[162:163] op_sel_hi:[0,1]
	v_pk_mul_f32 v[118:119], v[118:119], v[126:127]
	v_pk_mul_f32 v[116:117], v[116:117], v[124:125]
	v_pk_mul_f32 v[120:121], v[152:153], v[158:159] op_sel_hi:[0,1]
	v_pk_mul_f32 v[114:115], v[114:115], v[122:123]
	ds_read2_b32 v[140:141], v140 offset0:160 offset1:176
	v_pk_mul_f32 v[112:113], v[112:113], v[120:121]
	v_cvt_pk_bf16_f32 v116, v116, v117
	v_cvt_pk_bf16_f32 v117, v118, v119
	v_ashrrev_i32_e32 v155, 31, v154
	v_cvt_pk_bf16_f32 v118, v112, v113
	v_cvt_pk_bf16_f32 v119, v114, v115
	v_fmamk_f32 v114, v153, 0x3a000000, v218
	v_rsq_f32_e32 v124, v114
	v_mov_b64_e32 v[112:113], s[6:7]
	s_movk_i32 s13, 0x2c00
	v_mad_i64_i32 v[120:121], s[24:25], v151, s13, v[112:113]
	v_lshlrev_b64 v[114:115], 1, v[154:155]
	v_lshl_add_u64 v[120:121], v[120:121], 0, v[114:115]
	v_mul_f32_e32 v122, 0xbfb8aa3b, v124
	v_mul_f32_e32 v125, v104, v122
	global_store_dwordx4 v[120:121], v[116:119], off sc1
	v_mul_f32_e32 v123, v108, v122
	v_exp_f32_e32 v125, v125
	v_mul_f32_e32 v118, v109, v122
	v_exp_f32_e32 v119, v118
	v_mul_f32_e32 v118, v105, v122
	v_exp_f32_e32 v123, v123
	v_exp_f32_e32 v120, v118
	v_add_f32_e32 v117, 1.0, v125
	v_mul_f32_e32 v121, v106, v122
	v_add_f32_e32 v116, 1.0, v123
	v_rcp_f32_e32 v118, v117
	v_add_f32_e32 v117, 1.0, v119
	v_add_f32_e32 v119, 1.0, v120
	v_mul_f32_e32 v120, v110, v122
	v_exp_f32_e32 v121, v121
	v_mul_f32_e32 v123, v111, v122
	v_mul_f32_e32 v122, v107, v122
	v_exp_f32_e32 v123, v123
	v_exp_f32_e32 v125, v122
	v_add_f32_e32 v121, 1.0, v121
	v_rcp_f32_e32 v116, v116
	v_rcp_f32_e32 v117, v117
	v_exp_f32_e32 v120, v120
	v_rcp_f32_e32 v122, v121
	v_add_f32_e32 v121, 1.0, v123
	v_add_f32_e32 v123, 1.0, v125
	v_rcp_f32_e32 v119, v119
	v_rcp_f32_e32 v123, v123
	v_or_b32_e32 v125, 16, v151
	v_mul_f32_e32 v124, v124, v124
	v_add_f32_e32 v120, 1.0, v120
	v_pk_mul_f32 v[100:101], v[108:109], v[100:101]
	v_pk_mul_f32 v[108:109], v[124:125], v[116:117] op_sel_hi:[0,1]
	v_rcp_f32_e32 v120, v120
	v_rcp_f32_e32 v121, v121
	v_pk_mul_f32 v[100:101], v[100:101], v[108:109]
	v_pk_mul_f32 v[98:99], v[106:107], v[98:99]
	v_pk_mul_f32 v[96:97], v[104:105], v[96:97]
	v_pk_mul_f32 v[104:105], v[124:125], v[118:119] op_sel_hi:[0,1]
	v_pk_mul_f32 v[106:107], v[124:125], v[122:123] op_sel_hi:[0,1]
	v_pk_mul_f32 v[106:107], v[98:99], v[106:107]
	v_pk_mul_f32 v[98:99], v[96:97], v[104:105]
	v_cvt_pk_bf16_f32 v96, v100, v101
	s_waitcnt lgkmcnt(0)
	v_fmamk_f32 v100, v144, 0x3a000000, v218
	v_rsq_f32_e32 v104, v100
	v_pk_mul_f32 v[102:103], v[110:111], v[102:103]
	v_pk_mul_f32 v[110:111], v[124:125], v[120:121] op_sel_hi:[0,1]
	v_pk_mul_f32 v[102:103], v[102:103], v[110:111]
	v_mad_i64_i32 v[100:101], s[24:25], v125, s13, v[112:113]
	v_cvt_pk_bf16_f32 v97, v102, v103
	v_cvt_pk_bf16_f32 v98, v98, v99
	v_lshl_add_u64 v[100:101], v[100:101], 0, v[114:115]
	v_mul_f32_e32 v102, 0xbfb8aa3b, v104
	v_cvt_pk_bf16_f32 v99, v106, v107
	v_mul_f32_e32 v105, v88, v102
	global_store_dwordx4 v[100:101], v[96:99], off sc1
	v_mul_f32_e32 v103, v92, v102
	v_exp_f32_e32 v105, v105
	v_mul_f32_e32 v98, v93, v102
	v_exp_f32_e32 v99, v98
	v_mul_f32_e32 v98, v89, v102
	v_exp_f32_e32 v103, v103
	v_exp_f32_e32 v100, v98
	v_add_f32_e32 v97, 1.0, v105
	v_mul_f32_e32 v101, v90, v102
	v_add_f32_e32 v96, 1.0, v103
	v_rcp_f32_e32 v98, v97
	v_add_f32_e32 v97, 1.0, v99
	v_add_f32_e32 v99, 1.0, v100
	v_mul_f32_e32 v100, v94, v102
	v_exp_f32_e32 v101, v101
	v_mul_f32_e32 v103, v95, v102
	v_mul_f32_e32 v102, v91, v102
	v_exp_f32_e32 v103, v103
	v_exp_f32_e32 v105, v102
	v_add_f32_e32 v101, 1.0, v101
	v_rcp_f32_e32 v96, v96
	v_rcp_f32_e32 v97, v97
	v_exp_f32_e32 v100, v100
	v_rcp_f32_e32 v102, v101
	v_add_f32_e32 v101, 1.0, v103
	v_add_f32_e32 v103, 1.0, v105
	v_rcp_f32_e32 v99, v99
	v_rcp_f32_e32 v103, v103
	v_or_b32_e32 v105, 32, v151
	v_mul_f32_e32 v104, v104, v104
	v_add_f32_e32 v100, 1.0, v100
	v_pk_mul_f32 v[84:85], v[92:93], v[84:85]
; __device__ __forceinline__ unsigned cvt_pk_bf16(float lo, float hi) { unsigned r; asm volatile("v_cvt_pk_bf16_f32 %0, %1, %2" : "=v"(r) : "v"(lo), "v"(hi)); return r; }
;     __device__ __forceinline__ void operator()(const f32x4 (&acc)[2][2][4][2], const Unit& u, int wr, int wc, int fr, int fq, const float (&sv)[8]) const {
;     ...
;             for (int m = 0; m < 4; ++m) {
;                 const int row = row0 + ai * HALF + m * 16;
;                 const float rinv = __builtin_amdgcn_rsqf(sv[ai * 4 + m] * (1.f / DM) + EPS), rneg = rinv * -1.44269504f, r2 = rinv * rinv;
;                 const f32x4 g0 = acc[ai][0][m][0], g1 = acc[ai][0][m][1], u0 = acc[ai][1][m][0], u1 = acc[ai][1][m][1];
;                 f32x4 e0, e1;
; #pragma unroll
;                 for (int j = 0; j < 4; ++j) { e0[j] = __builtin_amdgcn_rcpf(1.f + __builtin_amdgcn_exp2f(g0[j] * rneg)); e1[j] = __builtin_amdgcn_rcpf(1.f + __builtin_amdgcn_exp2f(g1[j] * rneg)); }
;                 const f32x4 a0 = (g0 * u0) * (e0 * r2), a1 = (g1 * u1) * (e1 * r2);
;                 u32x4 w;
;                 w.x = cvt_pk_bf16(a0[0], a0[1]); w.y = cvt_pk_bf16(a0[2], a0[3]); w.z = cvt_pk_bf16(a1[0], a1[1]); w.w = cvt_pk_bf16(a1[2], a1[3]);
;                 *(u32x4*)(O + (size_t)row * DFF + col0) = w;
;             }
	v_pk_mul_f32 v[92:93], v[104:105], v[96:97] op_sel_hi:[0,1]
	v_rcp_f32_e32 v100, v100
	v_rcp_f32_e32 v101, v101
	v_pk_mul_f32 v[84:85], v[84:85], v[92:93]
	v_pk_mul_f32 v[82:83], v[90:91], v[82:83]
	v_pk_mul_f32 v[80:81], v[88:89], v[80:81]
	v_pk_mul_f32 v[88:89], v[104:105], v[98:99] op_sel_hi:[0,1]
	v_pk_mul_f32 v[90:91], v[104:105], v[102:103] op_sel_hi:[0,1]
	v_pk_mul_f32 v[90:91], v[82:83], v[90:91]
	v_pk_mul_f32 v[82:83], v[80:81], v[88:89]
	v_cvt_pk_bf16_f32 v80, v84, v85
	v_fmamk_f32 v84, v145, 0x3a000000, v218
	v_rsq_f32_e32 v88, v84
	v_pk_mul_f32 v[86:87], v[94:95], v[86:87]
	v_pk_mul_f32 v[94:95], v[104:105], v[100:101] op_sel_hi:[0,1]
	v_pk_mul_f32 v[86:87], v[86:87], v[94:95]
	v_mad_i64_i32 v[84:85], s[24:25], v105, s13, v[112:113]
	v_cvt_pk_bf16_f32 v81, v86, v87
	v_cvt_pk_bf16_f32 v82, v82, v83
	v_lshl_add_u64 v[84:85], v[84:85], 0, v[114:115]
	v_mul_f32_e32 v86, 0xbfb8aa3b, v88
	v_cvt_pk_bf16_f32 v83, v90, v91
	v_mul_f32_e32 v89, v72, v86
	global_store_dwordx4 v[84:85], v[80:83], off sc1
	v_mul_f32_e32 v87, v76, v86
	v_exp_f32_e32 v89, v89
	v_mul_f32_e32 v82, v77, v86
	v_exp_f32_e32 v83, v82
	v_mul_f32_e32 v82, v73, v86
	v_exp_f32_e32 v87, v87
	v_exp_f32_e32 v84, v82
	v_add_f32_e32 v81, 1.0, v89
	v_mul_f32_e32 v85, v74, v86
	v_add_f32_e32 v80, 1.0, v87
	v_rcp_f32_e32 v82, v81
	v_add_f32_e32 v81, 1.0, v83
	v_add_f32_e32 v83, 1.0, v84
	v_mul_f32_e32 v84, v78, v86
	v_exp_f32_e32 v85, v85
	v_mul_f32_e32 v87, v79, v86
	v_mul_f32_e32 v86, v75, v86
	v_exp_f32_e32 v87, v87
	v_exp_f32_e32 v89, v86
	v_add_f32_e32 v85, 1.0, v85
	v_rcp_f32_e32 v80, v80
	v_rcp_f32_e32 v81, v81
	v_rcp_f32_e32 v86, v85
	v_add_f32_e32 v85, 1.0, v87
	v_add_f32_e32 v87, 1.0, v89
	v_exp_f32_e32 v84, v84
	v_rcp_f32_e32 v83, v83
	v_rcp_f32_e32 v87, v87
	v_or_b32_e32 v89, 48, v151
	v_mul_f32_e32 v88, v88, v88
	v_pk_mul_f32 v[68:69], v[76:77], v[68:69]
	v_pk_mul_f32 v[76:77], v[88:89], v[80:81] op_sel_hi:[0,1]
	v_add_f32_e32 v84, 1.0, v84
	v_pk_mul_f32 v[68:69], v[68:69], v[76:77]
	v_pk_mul_f32 v[66:67], v[74:75], v[66:67]
	v_pk_mul_f32 v[64:65], v[72:73], v[64:65]
	v_pk_mul_f32 v[72:73], v[88:89], v[82:83] op_sel_hi:[0,1]
	v_pk_mul_f32 v[74:75], v[88:89], v[86:87] op_sel_hi:[0,1]
	v_rcp_f32_e32 v84, v84
	v_rcp_f32_e32 v85, v85
	v_pk_mul_f32 v[74:75], v[66:67], v[74:75]
	v_pk_mul_f32 v[66:67], v[64:65], v[72:73]
	v_cvt_pk_bf16_f32 v64, v68, v69
	v_fmamk_f32 v68, v142, 0x3a000000, v218
	v_rsq_f32_e32 v72, v68
	v_mad_i64_i32 v[68:69], s[24:25], v89, s13, v[112:113]
	v_pk_mul_f32 v[70:71], v[78:79], v[70:71]
	v_pk_mul_f32 v[78:79], v[88:89], v[84:85] op_sel_hi:[0,1]
	v_lshl_add_u64 v[68:69], v[68:69], 0, v[114:115]
	v_pk_mul_f32 v[70:71], v[70:71], v[78:79]
	v_add_u32_e32 v73, 0x80, v151
	v_cvt_pk_bf16_f32 v65, v70, v71
	v_cvt_pk_bf16_f32 v66, v66, v67
	v_cvt_pk_bf16_f32 v67, v74, v75
	global_store_dwordx4 v[68:69], v[64:67], off sc1
	v_mul_f32_e32 v69, 0xbfb8aa3b, v72
	v_mul_f32_e32 v70, v50, v69
	v_mul_f32_e32 v65, v48, v69
	v_mul_f32_e32 v66, v53, v69
	v_exp_f32_e32 v65, v65
	v_exp_f32_e32 v67, v66
	v_mul_f32_e32 v66, v49, v69
	v_exp_f32_e32 v68, v66
	v_mul_f32_e32 v64, v52, v69
	v_add_f32_e32 v65, 1.0, v65
	v_exp_f32_e32 v64, v64
	v_rcp_f32_e32 v66, v65
	v_add_f32_e32 v65, 1.0, v67
	v_add_f32_e32 v67, 1.0, v68
	v_mul_f32_e32 v68, v54, v69
	v_mul_f32_e32 v71, v55, v69
	v_mul_f32_e32 v69, v51, v69
	v_exp_f32_e32 v70, v70
	v_exp_f32_e32 v71, v71
	v_exp_f32_e32 v74, v69
	v_add_f32_e32 v64, 1.0, v64
	v_rcp_f32_e32 v64, v64
	v_rcp_f32_e32 v65, v65
	v_exp_f32_e32 v68, v68
	v_add_f32_e32 v70, 1.0, v70
	v_add_f32_e32 v69, 1.0, v71
	v_add_f32_e32 v71, 1.0, v74
	v_rcp_f32_e32 v67, v67
	v_rcp_f32_e32 v70, v70
	v_rcp_f32_e32 v71, v71
	v_mul_f32_e32 v72, v72, v72
	v_add_f32_e32 v68, 1.0, v68
	v_pk_mul_f32 v[52:53], v[52:53], v[60:61]
	v_pk_mul_f32 v[60:61], v[72:73], v[64:65] op_sel_hi:[0,1]
	v_rcp_f32_e32 v68, v68
	v_rcp_f32_e32 v69, v69
	v_pk_mul_f32 v[52:53], v[52:53], v[60:61]
	v_pk_mul_f32 v[50:51], v[50:51], v[58:59]
	v_pk_mul_f32 v[48:49], v[48:49], v[56:57]
	v_pk_mul_f32 v[56:57], v[72:73], v[66:67] op_sel_hi:[0,1]
	v_pk_mul_f32 v[58:59], v[72:73], v[70:71] op_sel_hi:[0,1]
	v_pk_mul_f32 v[58:59], v[50:51], v[58:59]
	v_pk_mul_f32 v[50:51], v[48:49], v[56:57]
	v_cvt_pk_bf16_f32 v48, v52, v53
	v_fmamk_f32 v52, v143, 0x3a000000, v218
	v_rsq_f32_e32 v56, v52
	v_pk_mul_f32 v[54:55], v[54:55], v[62:63]
	v_pk_mul_f32 v[62:63], v[72:73], v[68:69] op_sel_hi:[0,1]
	v_pk_mul_f32 v[54:55], v[54:55], v[62:63]
	v_mad_i64_i32 v[52:53], s[24:25], v73, s13, v[112:113]
	v_cvt_pk_bf16_f32 v49, v54, v55
	v_cvt_pk_bf16_f32 v50, v50, v51
	v_lshl_add_u64 v[52:53], v[52:53], 0, v[114:115]
	v_mul_f32_e32 v54, 0xbfb8aa3b, v56
	v_cvt_pk_bf16_f32 v51, v58, v59
	v_mul_f32_e32 v57, v24, v54
	global_store_dwordx4 v[52:53], v[48:51], off sc1
	v_mul_f32_e32 v55, v36, v54
	v_exp_f32_e32 v57, v57
	v_mul_f32_e32 v50, v37, v54
	v_exp_f32_e32 v51, v50
	v_mul_f32_e32 v50, v25, v54
	v_exp_f32_e32 v55, v55
	v_exp_f32_e32 v52, v50
	v_add_f32_e32 v49, 1.0, v57
	v_mul_f32_e32 v53, v26, v54
	v_add_f32_e32 v48, 1.0, v55
	v_rcp_f32_e32 v50, v49
	v_add_f32_e32 v49, 1.0, v51
	v_add_f32_e32 v51, 1.0, v52
	v_mul_f32_e32 v52, v38, v54
	v_exp_f32_e32 v53, v53
	v_mul_f32_e32 v55, v39, v54
	v_mul_f32_e32 v54, v27, v54
	v_exp_f32_e32 v55, v55
	v_exp_f32_e32 v57, v54
	v_add_f32_e32 v53, 1.0, v53
	v_rcp_f32_e32 v48, v48
	v_rcp_f32_e32 v49, v49
; __device__ __forceinline__ unsigned cvt_pk_bf16(float lo, float hi) { unsigned r; asm volatile("v_cvt_pk_bf16_f32 %0, %1, %2" : "=v"(r) : "v"(lo), "v"(hi)); return r; }
;     __device__ __forceinline__ void operator()(const f32x4 (&acc)[2][2][4][2], const Unit& u, int wr, int wc, int fr, int fq, const float (&sv)[8]) const {
;     ...
;             for (int m = 0; m < 4; ++m) {
;                 const int row = row0 + ai * HALF + m * 16;
;                 const float rinv = __builtin_amdgcn_rsqf(sv[ai * 4 + m] * (1.f / DM) + EPS), rneg = rinv * -1.44269504f, r2 = rinv * rinv;
;                 const f32x4 g0 = acc[ai][0][m][0], g1 = acc[ai][0][m][1], u0 = acc[ai][1][m][0], u1 = acc[ai][1][m][1];
;                 f32x4 e0, e1;
; #pragma unroll
;                 for (int j = 0; j < 4; ++j) { e0[j] = __builtin_amdgcn_rcpf(1.f + __builtin_amdgcn_exp2f(g0[j] * rneg)); e1[j] = __builtin_amdgcn_rcpf(1.f + __builtin_amdgcn_exp2f(g1[j] * rneg)); }
;                 const f32x4 a0 = (g0 * u0) * (e0 * r2), a1 = (g1 * u1) * (e1 * r2);
;                 u32x4 w;
;                 w.x = cvt_pk_bf16(a0[0], a0[1]); w.y = cvt_pk_bf16(a0[2], a0[3]); w.z = cvt_pk_bf16(a1[0], a1[1]); w.w = cvt_pk_bf16(a1[2], a1[3]);
;                 *(u32x4*)(O + (size_t)row * DFF + col0) = w;
;             }
; template <class Epi, class Sched, bool ALIGN_EPI = false, bool SP2 = false>
; __device__ __forceinline__ void gemm_phase(LAS unsigned char* lds, const Gemm g, const Sched& S, const Epi& E) {
;     ...
;         if constexpr (!Epi::AFTER_DRAIN) { E(acc, cur, wr, wc, fr, fq, sv); S.done(cur); }
	v_exp_f32_e32 v52, v52
	v_rcp_f32_e32 v54, v53
	v_add_f32_e32 v53, 1.0, v55
	v_add_f32_e32 v55, 1.0, v57
	v_rcp_f32_e32 v51, v51
	v_rcp_f32_e32 v55, v55
	v_add_u32_e32 v57, 0x90, v151
	v_mul_f32_e32 v56, v56, v56
	v_add_f32_e32 v52, 1.0, v52
	v_pk_mul_f32 v[36:37], v[36:37], v[44:45]
	v_pk_mul_f32 v[44:45], v[56:57], v[48:49] op_sel_hi:[0,1]
	v_rcp_f32_e32 v52, v52
	v_rcp_f32_e32 v53, v53
	v_pk_mul_f32 v[36:37], v[36:37], v[44:45]
	v_pk_mul_f32 v[26:27], v[26:27], v[42:43]
	v_pk_mul_f32 v[24:25], v[24:25], v[40:41]
	v_pk_mul_f32 v[40:41], v[56:57], v[50:51] op_sel_hi:[0,1]
	v_pk_mul_f32 v[42:43], v[56:57], v[54:55] op_sel_hi:[0,1]
	v_pk_mul_f32 v[42:43], v[26:27], v[42:43]
	v_pk_mul_f32 v[26:27], v[24:25], v[40:41]
	v_cvt_pk_bf16_f32 v24, v36, v37
	v_fmamk_f32 v36, v140, 0x3a000000, v218
	v_rsq_f32_e32 v40, v36
	v_pk_mul_f32 v[38:39], v[38:39], v[46:47]
	v_pk_mul_f32 v[46:47], v[56:57], v[52:53] op_sel_hi:[0,1]
	v_pk_mul_f32 v[38:39], v[38:39], v[46:47]
	v_mad_i64_i32 v[36:37], s[24:25], v57, s13, v[112:113]
	v_cvt_pk_bf16_f32 v25, v38, v39
	v_cvt_pk_bf16_f32 v26, v26, v27
	v_lshl_add_u64 v[36:37], v[36:37], 0, v[114:115]
	v_mul_f32_e32 v38, 0xbfb8aa3b, v40
	v_cvt_pk_bf16_f32 v27, v42, v43
	v_mul_f32_e32 v41, v8, v38
	global_store_dwordx4 v[36:37], v[24:27], off sc1
	v_mul_f32_e32 v39, v16, v38
	v_exp_f32_e32 v41, v41
	v_mul_f32_e32 v26, v17, v38
	v_exp_f32_e32 v27, v26
	v_mul_f32_e32 v26, v9, v38
	v_exp_f32_e32 v39, v39
	v_exp_f32_e32 v36, v26
	v_add_f32_e32 v25, 1.0, v41
	v_mul_f32_e32 v37, v10, v38
	v_add_f32_e32 v24, 1.0, v39
	v_rcp_f32_e32 v26, v25
	v_add_f32_e32 v25, 1.0, v27
	v_add_f32_e32 v27, 1.0, v36
	v_mul_f32_e32 v36, v18, v38
	v_exp_f32_e32 v37, v37
	v_mul_f32_e32 v39, v19, v38
	v_mul_f32_e32 v38, v11, v38
	v_exp_f32_e32 v39, v39
	v_exp_f32_e32 v41, v38
	v_add_f32_e32 v37, 1.0, v37
	v_rcp_f32_e32 v24, v24
	v_rcp_f32_e32 v25, v25
	v_exp_f32_e32 v36, v36
	v_rcp_f32_e32 v38, v37
	v_add_f32_e32 v37, 1.0, v39
	v_add_f32_e32 v39, 1.0, v41
	v_rcp_f32_e32 v27, v27
	v_rcp_f32_e32 v39, v39
	v_add_u32_e32 v41, 0xa0, v151
	v_mul_f32_e32 v40, v40, v40
	v_add_f32_e32 v36, 1.0, v36
	v_pk_mul_f32 v[16:17], v[16:17], v[32:33]
	v_pk_mul_f32 v[24:25], v[40:41], v[24:25] op_sel_hi:[0,1]
	v_rcp_f32_e32 v36, v36
	v_rcp_f32_e32 v37, v37
	v_pk_mul_f32 v[16:17], v[16:17], v[24:25]
	v_pk_mul_f32 v[10:11], v[10:11], v[30:31]
	v_pk_mul_f32 v[8:9], v[8:9], v[28:29]
	v_pk_mul_f32 v[24:25], v[40:41], v[26:27] op_sel_hi:[0,1]
	v_pk_mul_f32 v[26:27], v[40:41], v[38:39] op_sel_hi:[0,1]
	v_pk_mul_f32 v[26:27], v[10:11], v[26:27]
	v_pk_mul_f32 v[10:11], v[8:9], v[24:25]
	v_cvt_pk_bf16_f32 v8, v16, v17
	v_fmamk_f32 v16, v141, 0x3a000000, v218
	v_rsq_f32_e32 v24, v16
	v_pk_mul_f32 v[18:19], v[18:19], v[34:35]
	v_pk_mul_f32 v[32:33], v[40:41], v[36:37] op_sel_hi:[0,1]
	v_pk_mul_f32 v[18:19], v[18:19], v[32:33]
	v_mad_i64_i32 v[16:17], s[24:25], v41, s13, v[112:113]
	v_cvt_pk_bf16_f32 v9, v18, v19
	v_cvt_pk_bf16_f32 v10, v10, v11
	v_lshl_add_u64 v[16:17], v[16:17], 0, v[114:115]
	v_mul_f32_e32 v18, 0xbfb8aa3b, v24
	v_cvt_pk_bf16_f32 v11, v26, v27
	v_mul_f32_e32 v25, v0, v18
	global_store_dwordx4 v[16:17], v[8:11], off sc1
	v_mul_f32_e32 v19, v4, v18
	v_exp_f32_e32 v25, v25
	v_mul_f32_e32 v10, v5, v18
	v_exp_f32_e32 v11, v10
	v_mul_f32_e32 v10, v1, v18
	v_exp_f32_e32 v19, v19
	v_exp_f32_e32 v16, v10
	v_add_f32_e32 v9, 1.0, v25
	v_mul_f32_e32 v17, v2, v18
	v_add_f32_e32 v8, 1.0, v19
	v_rcp_f32_e32 v10, v9
	v_add_f32_e32 v9, 1.0, v11
	v_add_f32_e32 v11, 1.0, v16
	v_mul_f32_e32 v16, v6, v18
	v_exp_f32_e32 v17, v17
	v_mul_f32_e32 v19, v7, v18
	v_mul_f32_e32 v18, v3, v18
	v_exp_f32_e32 v19, v19
	v_exp_f32_e32 v25, v18
	v_exp_f32_e32 v16, v16
	v_add_f32_e32 v17, 1.0, v17
	v_rcp_f32_e32 v8, v8
	v_rcp_f32_e32 v9, v9
	v_rcp_f32_e32 v18, v17
	v_add_f32_e32 v17, 1.0, v19
	v_add_f32_e32 v19, 1.0, v25
	v_rcp_f32_e32 v11, v11
	v_rcp_f32_e32 v19, v19
	v_add_f32_e32 v16, 1.0, v16
	v_rcp_f32_e32 v16, v16
	v_rcp_f32_e32 v17, v17
	v_add_u32_e32 v25, 0xb0, v151
	v_mul_f32_e32 v24, v24, v24
	v_pk_mul_f32 v[4:5], v[4:5], v[20:21]
	v_pk_mul_f32 v[8:9], v[24:25], v[8:9] op_sel_hi:[0,1]
	v_pk_mul_f32 v[4:5], v[4:5], v[8:9]
	v_pk_mul_f32 v[2:3], v[2:3], v[14:15]
	v_pk_mul_f32 v[0:1], v[0:1], v[12:13]
	v_pk_mul_f32 v[8:9], v[24:25], v[10:11] op_sel_hi:[0,1]
	v_pk_mul_f32 v[10:11], v[24:25], v[18:19] op_sel_hi:[0,1]
	v_pk_mul_f32 v[10:11], v[2:3], v[10:11]
	v_pk_mul_f32 v[2:3], v[0:1], v[8:9]
	v_cvt_pk_bf16_f32 v0, v4, v5
	v_mad_i64_i32 v[4:5], s[24:25], v25, s13, v[112:113]
	v_pk_mul_f32 v[6:7], v[6:7], v[22:23]
	v_pk_mul_f32 v[16:17], v[24:25], v[16:17] op_sel_hi:[0,1]
	v_lshl_add_u64 v[4:5], v[4:5], 0, v[114:115]
	s_andn2_b64 vcc, exec, s[36:37]
	s_mov_b64 s[24:25], -1
	v_pk_mul_f32 v[6:7], v[6:7], v[16:17]
	s_nop 0
	v_cvt_pk_bf16_f32 v1, v6, v7
	v_cvt_pk_bf16_f32 v2, v2, v3
	v_cvt_pk_bf16_f32 v3, v10, v11
	global_store_dwordx4 v[4:5], v[0:3], off sc1
	s_cmp_lg_u32 s51, 10
	s_cbranch_scc1 .Lpa_ea_skip
	s_waitcnt vmcnt(0)
	s_barrier
	v_cmp_eq_u32_e32 vcc, 0, v216
	s_and_saveexec_b64 s[100:101], vcc
	s_cbranch_execz .Lpa_ea_done
	buffer_wbl2 sc1
	v_readlane_b32 vcc_lo, v246, 29
	s_lshl_b32 vcc_lo, vcc_lo, 6
	s_and_b32 vcc_hi, s65, 7
	s_lshl_b32 vcc_hi, vcc_hi, 2
	s_add_u32 vcc_lo, vcc_lo, vcc_hi
	s_add_u32 vcc_lo, vcc_lo, 0x83600
	v_mov_b32_e32 v2, vcc_lo
	v_mov_b32_e32 v4, 1
	s_waitcnt vmcnt(0)
	global_atomic_add v2, v4, s[98:99]
